# full stack: S2 schedule + prio 4-7 + generic grid loop + proj_a/proj_b barrier removed + unit-end store-wait relax + slot-loop back-edge rotation + 4-row interleaved combine
# speedup vs baseline: 1.0087x; 1.0087x over previous
; __device__ __forceinline__ float bf_lo(unsigned w) { return __uint_as_float(w << 16); }
; __device__ __forceinline__ float bf_hi(unsigned w) { return __uint_as_float(w & 0xffff0000u); }
; __device__ __forceinline__ void attn_phase(LAS unsigned char* lds, unsigned char* ws, int l) {
;     ...
;             for (int r = 0; r < 32; ++r) { const size_t t = (size_t)b * SEQ + qblk * 256 + wv * 32 + r;
;                 const u32x2 a = *(const u32x2*)(O12 + t * 4096 + h * 256 + 4 * lane), bb = *(const u32x2*)(O12 + t * 4096 + 2048 + h * 256 + 4 * lane);
;                 f32x4 o = (f32x4){bf_lo(a.x), bf_hi(a.x), bf_lo(a.y), bf_hi(a.y)} - (f32x4){bf_lo(bb.x), bf_hi(bb.x), bf_lo(bb.y), bf_hi(bb.y)} * lam;
;                 const float ss = wave_sum(o[0] * o[0] + o[1] * o[1] + o[2] * o[2] + o[3] * o[3]);
;                 const float rs = 1.0f / sqrtf(ss * (1.0f / 256.0f) + SUBLN_EPS);
.Lcomb_nopf:
	v_lshlrev_b32_e32 v18, 16, v28
	v_and_b32_e32 v19, 0xffff0000, v28
	v_lshlrev_b32_e32 v20, 16, v29
	v_and_b32_e32 v21, 0xffff0000, v29
	v_lshlrev_b32_e32 v22, 16, v30
	v_and_b32_e32 v23, 0xffff0000, v30
	v_lshlrev_b32_e32 v24, 16, v31
	v_and_b32_e32 v25, 0xffff0000, v31
	v_pk_fma_f32 v[30:31], v[26:27], v[24:25], v[20:21]
	v_pk_fma_f32 v[28:29], v[12:13], v[22:23], v[18:19] neg_lo:[1,0,0] neg_hi:[1,0,0]
	v_pk_mul_f32 v[18:19], v[30:31], v[30:31]
	v_mul_f32_e32 v20, v29, v29
	v_fmac_f32_e32 v20, v28, v28
	v_add_f32_e32 v18, v18, v20
	v_add_f32_e32 v60, v19, v18
	v_lshlrev_b32_e32 v18, 16, v32
	v_and_b32_e32 v19, 0xffff0000, v32
	v_lshlrev_b32_e32 v20, 16, v33
	v_and_b32_e32 v21, 0xffff0000, v33
	v_lshlrev_b32_e32 v22, 16, v34
	v_and_b32_e32 v23, 0xffff0000, v34
	v_lshlrev_b32_e32 v24, 16, v35
	v_and_b32_e32 v25, 0xffff0000, v35
	v_pk_fma_f32 v[34:35], v[26:27], v[24:25], v[20:21]
	v_pk_fma_f32 v[32:33], v[12:13], v[22:23], v[18:19] neg_lo:[1,0,0] neg_hi:[1,0,0]
	v_pk_mul_f32 v[18:19], v[34:35], v[34:35]
	v_mul_f32_e32 v20, v33, v33
	v_fmac_f32_e32 v20, v32, v32
	v_add_f32_e32 v18, v18, v20
	v_add_f32_e32 v61, v19, v18
	v_lshlrev_b32_e32 v18, 16, v36
	v_and_b32_e32 v19, 0xffff0000, v36
	v_lshlrev_b32_e32 v20, 16, v37
	v_and_b32_e32 v21, 0xffff0000, v37
	v_lshlrev_b32_e32 v22, 16, v38
	v_and_b32_e32 v23, 0xffff0000, v38
	v_lshlrev_b32_e32 v24, 16, v39
	v_and_b32_e32 v25, 0xffff0000, v39
	v_pk_fma_f32 v[38:39], v[26:27], v[24:25], v[20:21]
	v_pk_fma_f32 v[36:37], v[12:13], v[22:23], v[18:19] neg_lo:[1,0,0] neg_hi:[1,0,0]
	v_pk_mul_f32 v[18:19], v[38:39], v[38:39]
	v_mul_f32_e32 v20, v37, v37
	v_fmac_f32_e32 v20, v36, v36
	v_add_f32_e32 v18, v18, v20
	v_add_f32_e32 v62, v19, v18
	v_lshlrev_b32_e32 v18, 16, v40
	v_and_b32_e32 v19, 0xffff0000, v40
	v_lshlrev_b32_e32 v20, 16, v41
	v_and_b32_e32 v21, 0xffff0000, v41
	v_lshlrev_b32_e32 v22, 16, v42
	v_and_b32_e32 v23, 0xffff0000, v42
	v_lshlrev_b32_e32 v24, 16, v43
	v_and_b32_e32 v25, 0xffff0000, v43
	v_pk_fma_f32 v[42:43], v[26:27], v[24:25], v[20:21]
	v_pk_fma_f32 v[40:41], v[12:13], v[22:23], v[18:19] neg_lo:[1,0,0] neg_hi:[1,0,0]
	v_pk_mul_f32 v[18:19], v[42:43], v[42:43]
	v_mul_f32_e32 v20, v41, v41
	v_fmac_f32_e32 v20, v40, v40
	v_add_f32_e32 v18, v18, v20
	v_add_f32_e32 v63, v19, v18
	ds_bpermute_b32 v18, v0, v60
	ds_bpermute_b32 v19, v0, v61
	ds_bpermute_b32 v20, v0, v62
	ds_bpermute_b32 v21, v0, v63
	s_waitcnt lgkmcnt(0)
	v_add_f32_e32 v60, v60, v18
	v_add_f32_e32 v61, v61, v19
	v_add_f32_e32 v62, v62, v20
	v_add_f32_e32 v63, v63, v21
	ds_bpermute_b32 v18, v14, v60
	ds_bpermute_b32 v19, v14, v61
	ds_bpermute_b32 v20, v14, v62
	ds_bpermute_b32 v21, v14, v63
	s_waitcnt lgkmcnt(0)
	v_add_f32_e32 v60, v60, v18
	v_add_f32_e32 v61, v61, v19
	v_add_f32_e32 v62, v62, v20
	v_add_f32_e32 v63, v63, v21
	ds_bpermute_b32 v18, v15, v60
	ds_bpermute_b32 v19, v15, v61
	ds_bpermute_b32 v20, v15, v62
	ds_bpermute_b32 v21, v15, v63
	s_waitcnt lgkmcnt(0)
	v_add_f32_e32 v60, v60, v18
	v_add_f32_e32 v61, v61, v19
	v_add_f32_e32 v62, v62, v20
	v_add_f32_e32 v63, v63, v21
	ds_bpermute_b32 v18, v16, v60
	ds_bpermute_b32 v19, v16, v61
	ds_bpermute_b32 v20, v16, v62
	ds_bpermute_b32 v21, v16, v63
	s_waitcnt lgkmcnt(0)
	v_add_f32_e32 v60, v60, v18
	v_add_f32_e32 v61, v61, v19
	v_add_f32_e32 v62, v62, v20
	v_add_f32_e32 v63, v63, v21
	ds_bpermute_b32 v18, v17, v60
	ds_bpermute_b32 v19, v17, v61
	ds_bpermute_b32 v20, v17, v62
	ds_bpermute_b32 v21, v17, v63
	s_waitcnt lgkmcnt(0)
	v_add_f32_e32 v60, v60, v18
	v_add_f32_e32 v61, v61, v19
	v_add_f32_e32 v62, v62, v20
	v_add_f32_e32 v63, v63, v21
	ds_bpermute_b32 v18, v131, v60
	ds_bpermute_b32 v19, v131, v61
	ds_bpermute_b32 v20, v131, v62
	ds_bpermute_b32 v21, v131, v63
	s_waitcnt lgkmcnt(0)
; __device__ __forceinline__ unsigned pk2(float lo, float hi) { f32x2 v = {lo, hi}; bf16x2_t b = __builtin_convertvector(v, bf16x2_t); return __builtin_bit_cast(unsigned, b); }
; __device__ __forceinline__ void attn_phase(LAS unsigned char* lds, unsigned char* ws, int l) {
;     ...
;     for (int vb = blockIdx.x; vb < 256; vb += gridDim.x) {
;         const int v2 = (vb & 7) * 32 + (vb >> 3);
;         const int j = v2 & 7, h = (v2 >> 3) & 7, b = v2 >> 6;
;     ...
;                 const float rs = 1.0f / sqrtf(ss * (1.0f / 256.0f) + SUBLN_EPS);
;                 o = o * rs * g;
;                 u32x2 w; w.x = pk2(o[0], o[1]); w.y = pk2(o[2], o[3]);
;                 *(u32x2*)(OB + t * DM + h * 256 + 4 * lane) = w; }
	v_add_f32_e32 v60, v60, v18
	v_add_f32_e32 v61, v61, v19
	v_add_f32_e32 v62, v62, v20
	v_add_f32_e32 v63, v63, v21
	v_fmamk_f32 v22, v60, 0x3b800000, v225
	v_cmp_gt_f32_e32 vcc, s91, v22
	v_mul_f32_e32 v23, 0x4f800000, v22
	s_nop 0
	v_cndmask_b32_e32 v22, v22, v23, vcc
	v_sqrt_f32_e32 v23, v22
	s_nop 0
	v_add_u32_e32 v24, -1, v23
	v_fma_f32 v25, -v24, v23, v22
	v_cmp_ge_f32_e64 s[0:1], 0, v25
	v_add_u32_e32 v25, 1, v23
	s_nop 0
	v_cndmask_b32_e64 v24, v23, v24, s[0:1]
	v_fma_f32 v23, -v25, v23, v22
	v_cmp_lt_f32_e64 s[0:1], 0, v23
	s_nop 1
	v_cndmask_b32_e64 v23, v24, v25, s[0:1]
	v_mul_f32_e32 v24, 0x37800000, v23
	v_cndmask_b32_e32 v23, v23, v24, vcc
	v_cmp_class_f32_e32 vcc, v22, v226
	s_nop 1
	v_cndmask_b32_e32 v22, v23, v22, vcc
	v_div_scale_f32 v23, s[0:1], v22, v22, 1.0
	v_rcp_f32_e32 v24, v23
	s_nop 1
	v_fma_f32 v25, -v23, v24, 1.0
	v_fmac_f32_e32 v24, v25, v24
	v_div_scale_f32 v25, vcc, 1.0, v22, 1.0
	v_mul_f32_e32 v64, v25, v24
	v_fma_f32 v65, -v23, v64, v25
	v_fmac_f32_e32 v64, v65, v24
	v_fma_f32 v23, -v23, v64, v25
	v_div_fmas_f32 v23, v23, v24, v64
	v_div_fixup_f32 v22, v23, v22, 1.0
	v_pk_mul_f32 v[28:29], v[28:29], v[22:23] op_sel_hi:[1,0]
	v_pk_mul_f32 v[30:31], v[30:31], v[22:23] op_sel_hi:[1,0]
	v_pk_mul_f32 v[28:29], v[10:11], v[28:29]
	v_pk_mul_f32 v[30:31], v[8:9], v[30:31]
	v_cvt_pk_bf16_f32 v28, v28, v29
	v_cvt_pk_bf16_f32 v29, v30, v31
	v_lshl_add_u64 v[18:19], v[4:5], 0, s[36:37]
	global_store_dwordx2 v[18:19], v[28:29], off
	v_fmamk_f32 v22, v61, 0x3b800000, v225
	v_cmp_gt_f32_e32 vcc, s91, v22
	v_mul_f32_e32 v23, 0x4f800000, v22
	s_nop 0
	v_cndmask_b32_e32 v22, v22, v23, vcc
	v_sqrt_f32_e32 v23, v22
	s_nop 0
	v_add_u32_e32 v24, -1, v23
	v_fma_f32 v25, -v24, v23, v22
	v_cmp_ge_f32_e64 s[0:1], 0, v25
	v_add_u32_e32 v25, 1, v23
	s_nop 0
	v_cndmask_b32_e64 v24, v23, v24, s[0:1]
	v_fma_f32 v23, -v25, v23, v22
	v_cmp_lt_f32_e64 s[0:1], 0, v23
	s_nop 1
	v_cndmask_b32_e64 v23, v24, v25, s[0:1]
	v_mul_f32_e32 v24, 0x37800000, v23
	v_cndmask_b32_e32 v23, v23, v24, vcc
	v_cmp_class_f32_e32 vcc, v22, v226
	s_nop 1
	v_cndmask_b32_e32 v22, v23, v22, vcc
	v_div_scale_f32 v23, s[0:1], v22, v22, 1.0
	v_rcp_f32_e32 v24, v23
	s_nop 1
	v_fma_f32 v25, -v23, v24, 1.0
	v_fmac_f32_e32 v24, v25, v24
	v_div_scale_f32 v25, vcc, 1.0, v22, 1.0
	v_mul_f32_e32 v64, v25, v24
	v_fma_f32 v65, -v23, v64, v25
	v_fmac_f32_e32 v64, v65, v24
	v_fma_f32 v23, -v23, v64, v25
	v_div_fmas_f32 v23, v23, v24, v64
	v_div_fixup_f32 v22, v23, v22, 1.0
	v_pk_mul_f32 v[32:33], v[32:33], v[22:23] op_sel_hi:[1,0]
	v_pk_mul_f32 v[34:35], v[34:35], v[22:23] op_sel_hi:[1,0]
	v_pk_mul_f32 v[32:33], v[10:11], v[32:33]
	v_pk_mul_f32 v[34:35], v[8:9], v[34:35]
	v_cvt_pk_bf16_f32 v32, v32, v33
	v_cvt_pk_bf16_f32 v33, v34, v35
	s_add_u32 s0, s36, 0x1000
	s_addc_u32 s1, s37, 0
	v_lshl_add_u64 v[18:19], v[4:5], 0, s[0:1]
	global_store_dwordx2 v[18:19], v[32:33], off
	v_fmamk_f32 v22, v62, 0x3b800000, v225
	v_cmp_gt_f32_e32 vcc, s91, v22
	v_mul_f32_e32 v23, 0x4f800000, v22
	s_nop 0
	v_cndmask_b32_e32 v22, v22, v23, vcc
	v_sqrt_f32_e32 v23, v22
	s_nop 0
	v_add_u32_e32 v24, -1, v23
	v_fma_f32 v25, -v24, v23, v22
	v_cmp_ge_f32_e64 s[0:1], 0, v25
	v_add_u32_e32 v25, 1, v23
	s_nop 0
	v_cndmask_b32_e64 v24, v23, v24, s[0:1]
	v_fma_f32 v23, -v25, v23, v22
	v_cmp_lt_f32_e64 s[0:1], 0, v23
	s_nop 1
	v_cndmask_b32_e64 v23, v24, v25, s[0:1]
	v_mul_f32_e32 v24, 0x37800000, v23
	v_cndmask_b32_e32 v23, v23, v24, vcc
	v_cmp_class_f32_e32 vcc, v22, v226
	s_nop 1
	v_cndmask_b32_e32 v22, v23, v22, vcc
	v_div_scale_f32 v23, s[0:1], v22, v22, 1.0
	v_rcp_f32_e32 v24, v23
	s_nop 1
	v_fma_f32 v25, -v23, v24, 1.0
	v_fmac_f32_e32 v24, v25, v24
	v_div_scale_f32 v25, vcc, 1.0, v22, 1.0
	v_mul_f32_e32 v64, v25, v24
	v_fma_f32 v65, -v23, v64, v25
	v_fmac_f32_e32 v64, v65, v24
	v_fma_f32 v23, -v23, v64, v25
	v_div_fmas_f32 v23, v23, v24, v64
	v_div_fixup_f32 v22, v23, v22, 1.0
	v_pk_mul_f32 v[36:37], v[36:37], v[22:23] op_sel_hi:[1,0]
	v_pk_mul_f32 v[38:39], v[38:39], v[22:23] op_sel_hi:[1,0]
	v_pk_mul_f32 v[36:37], v[10:11], v[36:37]
	v_pk_mul_f32 v[38:39], v[8:9], v[38:39]
	v_cvt_pk_bf16_f32 v36, v36, v37
	v_cvt_pk_bf16_f32 v37, v38, v39
	s_add_u32 s0, s36, 0x2000
	s_addc_u32 s1, s37, 0
	v_lshl_add_u64 v[18:19], v[4:5], 0, s[0:1]
	global_store_dwordx2 v[18:19], v[36:37], off
	v_fmamk_f32 v22, v63, 0x3b800000, v225
	v_cmp_gt_f32_e32 vcc, s91, v22
	v_mul_f32_e32 v23, 0x4f800000, v22
	s_nop 0
	v_cndmask_b32_e32 v22, v22, v23, vcc
	v_sqrt_f32_e32 v23, v22
	s_nop 0
	v_add_u32_e32 v24, -1, v23
	v_fma_f32 v25, -v24, v23, v22
	v_cmp_ge_f32_e64 s[0:1], 0, v25
	v_add_u32_e32 v25, 1, v23
	s_nop 0
	v_cndmask_b32_e64 v24, v23, v24, s[0:1]
	v_fma_f32 v23, -v25, v23, v22
	v_cmp_lt_f32_e64 s[0:1], 0, v23
	s_nop 1
	v_cndmask_b32_e64 v23, v24, v25, s[0:1]
	v_mul_f32_e32 v24, 0x37800000, v23
	v_cndmask_b32_e32 v23, v23, v24, vcc
	v_cmp_class_f32_e32 vcc, v22, v226
	s_nop 1
	v_cndmask_b32_e32 v22, v23, v22, vcc
	v_div_scale_f32 v23, s[0:1], v22, v22, 1.0
	v_rcp_f32_e32 v24, v23
	s_nop 1
	v_fma_f32 v25, -v23, v24, 1.0
	v_fmac_f32_e32 v24, v25, v24
	v_div_scale_f32 v25, vcc, 1.0, v22, 1.0
	v_mul_f32_e32 v64, v25, v24
	v_fma_f32 v65, -v23, v64, v25
	v_fmac_f32_e32 v64, v65, v24
	v_fma_f32 v23, -v23, v64, v25
	v_div_fmas_f32 v23, v23, v24, v64
	v_div_fixup_f32 v22, v23, v22, 1.0
	v_pk_mul_f32 v[40:41], v[40:41], v[22:23] op_sel_hi:[1,0]
	v_pk_mul_f32 v[42:43], v[42:43], v[22:23] op_sel_hi:[1,0]
	v_pk_mul_f32 v[40:41], v[10:11], v[40:41]
	v_pk_mul_f32 v[42:43], v[8:9], v[42:43]
	v_cvt_pk_bf16_f32 v40, v40, v41
	v_cvt_pk_bf16_f32 v41, v42, v43
	s_add_u32 s0, s36, 0x3000
	s_addc_u32 s1, s37, 0
	v_lshl_add_u64 v[18:19], v[4:5], 0, s[0:1]
	global_store_dwordx2 v[18:19], v[40:41], off
	s_add_u32 s36, s36, 0x4000
	s_addc_u32 s37, s37, 0
	s_cmp_eq_u32 s36, 0x10000
	s_cbranch_scc0 .Lcomb_loop
	s_add_i32 s98, s98, 1
	s_cmp_lt_u32 s98, 4
	s_cbranch_scc1 .LBB0_249
	s_add_i32 s27, s27, s3
	s_mov_b32 s98, 0
	s_cmpk_gt_i32 s27, 0xff
	s_cbranch_scc0 .LBB0_249
	s_setprio 0
	v_readlane_b32 s48, v255, 6
	v_readlane_b32 s49, v255, 7
	v_readlane_b32 s93, v255, 12
	s_mov_b32 s40, s50
